# GEMM K-loop heads aligned to 64 bytes (all five), attention loops at 48/16
# baseline (speedup 1.0000x reference)
.LBB0_154:
	s_ashr_i32 s25, s24, 31
	s_lshl_b64 s[26:27], s[24:25], 19
	s_add_u32 s26, s34, s26
	s_addc_u32 s27, s35, s27
	s_and_b64 s[28:29], s[4:5], exec
	s_cselect_b32 s25, s27, s3
	s_cselect_b32 s48, s26, s2
	s_ashr_i32 s23, s22, 31
	s_lshl_b64 s[28:29], s[22:23], 19
	s_add_u32 s28, s33, s28
	s_addc_u32 s29, s36, s29
	s_and_b64 s[30:31], s[4:5], exec
	s_cselect_b32 s23, s29, s7
	s_cselect_b32 s49, s28, s6
	s_add_u32 s2, s2, 0x40080
	s_addc_u32 s3, s3, 0
	s_add_u32 s50, s6, 0x100
	v_mov_b32_e32 v0, 0
	s_addc_u32 s51, s7, 0
	s_mov_b32 s52, -2
	v_mov_b32_e32 v1, v0
	v_mov_b32_e32 v2, v0
	v_mov_b32_e32 v3, v0
	v_mov_b32_e32 v4, v0
	v_mov_b32_e32 v5, v0
	v_mov_b32_e32 v6, v0
	v_mov_b32_e32 v7, v0
	v_mov_b32_e32 v16, v0
	v_mov_b32_e32 v17, v0
	v_mov_b32_e32 v18, v0
	v_mov_b32_e32 v19, v0
	v_mov_b32_e32 v20, v0
	v_mov_b32_e32 v21, v0
	v_mov_b32_e32 v22, v0
	v_mov_b32_e32 v23, v0
	v_mov_b32_e32 v32, v0
	v_mov_b32_e32 v33, v0
	v_mov_b32_e32 v34, v0
	v_mov_b32_e32 v35, v0
	v_mov_b32_e32 v36, v0
	v_mov_b32_e32 v37, v0
	v_mov_b32_e32 v38, v0
	v_mov_b32_e32 v39, v0
	v_mov_b32_e32 v48, v0
	v_mov_b32_e32 v49, v0
	v_mov_b32_e32 v50, v0
	v_mov_b32_e32 v51, v0
	v_mov_b32_e32 v52, v0
	v_mov_b32_e32 v53, v0
	v_mov_b32_e32 v54, v0
	v_mov_b32_e32 v55, v0
	v_mov_b32_e32 v8, v0
	v_mov_b32_e32 v9, v0
	v_mov_b32_e32 v10, v0
	v_mov_b32_e32 v11, v0
	v_mov_b32_e32 v12, v0
	v_mov_b32_e32 v13, v0
	v_mov_b32_e32 v14, v0
	v_mov_b32_e32 v15, v0
	v_mov_b32_e32 v24, v0
	v_mov_b32_e32 v25, v0
	v_mov_b32_e32 v26, v0
	v_mov_b32_e32 v27, v0
	v_mov_b32_e32 v28, v0
	v_mov_b32_e32 v29, v0
	v_mov_b32_e32 v30, v0
	v_mov_b32_e32 v31, v0
	v_mov_b32_e32 v40, v0
	v_mov_b32_e32 v41, v0
	v_mov_b32_e32 v42, v0
	v_mov_b32_e32 v43, v0
	v_mov_b32_e32 v44, v0
	v_mov_b32_e32 v45, v0
	v_mov_b32_e32 v46, v0
	v_mov_b32_e32 v47, v0
	v_mov_b32_e32 v56, v0
	v_mov_b32_e32 v57, v0
	v_mov_b32_e32 v58, v0
	v_mov_b32_e32 v59, v0
	v_mov_b32_e32 v60, v0
	v_mov_b32_e32 v61, v0
	v_mov_b32_e32 v62, v0
	v_mov_b32_e32 v63, v0
	v_mov_b32_e32 v64, v0
	v_mov_b32_e32 v65, v0
	v_mov_b32_e32 v66, v0
	v_mov_b32_e32 v67, v0
	v_mov_b32_e32 v68, v0
	v_mov_b32_e32 v69, v0
	v_mov_b32_e32 v70, v0
	v_mov_b32_e32 v71, v0
	v_mov_b32_e32 v80, v0
	v_mov_b32_e32 v81, v0
	v_mov_b32_e32 v82, v0
	v_mov_b32_e32 v83, v0
	v_mov_b32_e32 v84, v0
	v_mov_b32_e32 v85, v0
	v_mov_b32_e32 v86, v0
	v_mov_b32_e32 v87, v0
	v_mov_b32_e32 v96, v0
	v_mov_b32_e32 v97, v0
	v_mov_b32_e32 v98, v0
	v_mov_b32_e32 v99, v0
	v_mov_b32_e32 v100, v0
	v_mov_b32_e32 v101, v0
	v_mov_b32_e32 v102, v0
	v_mov_b32_e32 v103, v0
	v_mov_b32_e32 v112, v0
	v_mov_b32_e32 v113, v0
	v_mov_b32_e32 v114, v0
	v_mov_b32_e32 v115, v0
	v_mov_b32_e32 v116, v0
	v_mov_b32_e32 v117, v0
	v_mov_b32_e32 v118, v0
	v_mov_b32_e32 v119, v0
	v_mov_b32_e32 v72, v0
	v_mov_b32_e32 v73, v0
	v_mov_b32_e32 v74, v0
	v_mov_b32_e32 v75, v0
	v_mov_b32_e32 v76, v0
	v_mov_b32_e32 v77, v0
	v_mov_b32_e32 v78, v0
	v_mov_b32_e32 v79, v0
	v_mov_b32_e32 v88, v0
	v_mov_b32_e32 v89, v0
	v_mov_b32_e32 v90, v0
	v_mov_b32_e32 v91, v0
	v_mov_b32_e32 v92, v0
	v_mov_b32_e32 v93, v0
	v_mov_b32_e32 v94, v0
	v_mov_b32_e32 v95, v0
	v_mov_b32_e32 v104, v0
	v_mov_b32_e32 v105, v0
	v_mov_b32_e32 v106, v0
	v_mov_b32_e32 v107, v0
	v_mov_b32_e32 v108, v0
	v_mov_b32_e32 v109, v0
	v_mov_b32_e32 v110, v0
	v_mov_b32_e32 v111, v0
	v_mov_b32_e32 v120, v0
	v_mov_b32_e32 v121, v0
	v_mov_b32_e32 v122, v0
	v_mov_b32_e32 v123, v0
	v_mov_b32_e32 v124, v0
	v_mov_b32_e32 v125, v0
	v_mov_b32_e32 v126, v0
	v_mov_b32_e32 v127, v0
	.p2align 6

.LBB0_224:
	s_ashr_i32 s11, s10, 31
	s_lshl_b64 s[12:13], s[10:11], 19
	s_add_u32 s12, s22, s12
	s_addc_u32 s13, s23, s13
	s_and_b64 s[14:15], s[4:5], exec
	s_cselect_b32 s11, s13, s17
	s_cselect_b32 s37, s12, s16
	s_ashr_i32 s9, s8, 31
	s_lshl_b64 s[14:15], s[8:9], 19
	s_add_u32 s14, s34, s14
	s_addc_u32 s15, s35, s15
	s_and_b64 s[20:21], s[4:5], exec
	s_cselect_b32 s9, s15, s19
	s_cselect_b32 s38, s14, s18
	s_add_u32 s16, s16, 0x40080
	s_addc_u32 s17, s17, 0
	s_add_u32 s39, s18, 0x100
	v_mov_b32_e32 v0, 0
	s_addc_u32 s40, s19, 0
	s_mov_b32 s41, -2
	v_mov_b32_e32 v1, v0
	v_mov_b32_e32 v2, v0
	v_mov_b32_e32 v3, v0
	v_mov_b32_e32 v4, v0
	v_mov_b32_e32 v5, v0
	v_mov_b32_e32 v6, v0
	v_mov_b32_e32 v7, v0
	v_mov_b32_e32 v8, v0
	v_mov_b32_e32 v9, v0
	v_mov_b32_e32 v10, v0
	v_mov_b32_e32 v11, v0
	v_mov_b32_e32 v12, v0
	v_mov_b32_e32 v13, v0
	v_mov_b32_e32 v14, v0
	v_mov_b32_e32 v15, v0
	v_mov_b32_e32 v24, v0
	v_mov_b32_e32 v25, v0
	v_mov_b32_e32 v26, v0
	v_mov_b32_e32 v27, v0
	v_mov_b32_e32 v28, v0
	v_mov_b32_e32 v29, v0
	v_mov_b32_e32 v30, v0
	v_mov_b32_e32 v31, v0
	v_mov_b32_e32 v40, v0
	v_mov_b32_e32 v41, v0
	v_mov_b32_e32 v42, v0
	v_mov_b32_e32 v43, v0
	v_mov_b32_e32 v44, v0
	v_mov_b32_e32 v45, v0
	v_mov_b32_e32 v46, v0
	v_mov_b32_e32 v47, v0
	v_mov_b32_e32 v16, v0
	v_mov_b32_e32 v17, v0
	v_mov_b32_e32 v18, v0
	v_mov_b32_e32 v19, v0
	v_mov_b32_e32 v20, v0
	v_mov_b32_e32 v21, v0
	v_mov_b32_e32 v22, v0
	v_mov_b32_e32 v23, v0
	v_mov_b32_e32 v32, v0
	v_mov_b32_e32 v33, v0
	v_mov_b32_e32 v34, v0
	v_mov_b32_e32 v35, v0
	v_mov_b32_e32 v36, v0
	v_mov_b32_e32 v37, v0
	v_mov_b32_e32 v38, v0
	v_mov_b32_e32 v39, v0
	v_mov_b32_e32 v48, v0
	v_mov_b32_e32 v49, v0
	v_mov_b32_e32 v50, v0
	v_mov_b32_e32 v51, v0
	v_mov_b32_e32 v52, v0
	v_mov_b32_e32 v53, v0
	v_mov_b32_e32 v54, v0
	v_mov_b32_e32 v55, v0
	v_mov_b32_e32 v56, v0
	v_mov_b32_e32 v57, v0
	v_mov_b32_e32 v58, v0
	v_mov_b32_e32 v59, v0
	v_mov_b32_e32 v60, v0
	v_mov_b32_e32 v61, v0
	v_mov_b32_e32 v62, v0
	v_mov_b32_e32 v63, v0
	v_mov_b32_e32 v64, v0
	v_mov_b32_e32 v65, v0
	v_mov_b32_e32 v66, v0
	v_mov_b32_e32 v67, v0
	v_mov_b32_e32 v68, v0
	v_mov_b32_e32 v69, v0
	v_mov_b32_e32 v70, v0
	v_mov_b32_e32 v71, v0
	v_mov_b32_e32 v72, v0
	v_mov_b32_e32 v73, v0
	v_mov_b32_e32 v74, v0
	v_mov_b32_e32 v75, v0
	v_mov_b32_e32 v76, v0
	v_mov_b32_e32 v77, v0
	v_mov_b32_e32 v78, v0
	v_mov_b32_e32 v79, v0
	v_mov_b32_e32 v88, v0
	v_mov_b32_e32 v89, v0
	v_mov_b32_e32 v90, v0
	v_mov_b32_e32 v91, v0
	v_mov_b32_e32 v92, v0
	v_mov_b32_e32 v93, v0
	v_mov_b32_e32 v94, v0
	v_mov_b32_e32 v95, v0
	v_mov_b32_e32 v104, v0
	v_mov_b32_e32 v105, v0
	v_mov_b32_e32 v106, v0
	v_mov_b32_e32 v107, v0
	v_mov_b32_e32 v108, v0
	v_mov_b32_e32 v109, v0
	v_mov_b32_e32 v110, v0
	v_mov_b32_e32 v111, v0
	v_mov_b32_e32 v80, v0
	v_mov_b32_e32 v81, v0
	v_mov_b32_e32 v82, v0
	v_mov_b32_e32 v83, v0
	v_mov_b32_e32 v84, v0
	v_mov_b32_e32 v85, v0
	v_mov_b32_e32 v86, v0
	v_mov_b32_e32 v87, v0
	v_mov_b32_e32 v96, v0
	v_mov_b32_e32 v97, v0
	v_mov_b32_e32 v98, v0
	v_mov_b32_e32 v99, v0
	v_mov_b32_e32 v100, v0
	v_mov_b32_e32 v101, v0
	v_mov_b32_e32 v102, v0
	v_mov_b32_e32 v103, v0
	v_mov_b32_e32 v112, v0
	v_mov_b32_e32 v113, v0
	v_mov_b32_e32 v114, v0
	v_mov_b32_e32 v115, v0
	v_mov_b32_e32 v116, v0
	v_mov_b32_e32 v117, v0
	v_mov_b32_e32 v118, v0
	v_mov_b32_e32 v119, v0
	v_mov_b32_e32 v120, v0
	v_mov_b32_e32 v121, v0
	v_mov_b32_e32 v122, v0
	v_mov_b32_e32 v123, v0
	v_mov_b32_e32 v124, v0
	v_mov_b32_e32 v125, v0
	v_mov_b32_e32 v126, v0
	v_mov_b32_e32 v127, v0
	.p2align 6

.LBB0_630:
	s_ashr_i32 s17, s16, 31
	s_lshl_b64 s[18:19], s[16:17], 19
	s_add_u32 s18, s28, s18
	s_addc_u32 s19, s29, s19
	s_and_b64 s[20:21], s[4:5], exec
	s_cselect_b32 s17, s19, s23
	s_cselect_b32 s43, s18, s22
	s_ashr_i32 s15, s14, 31
	s_lshl_b64 s[20:21], s[14:15], 19
	s_add_u32 s20, s30, s20
	s_addc_u32 s21, s31, s21
	s_and_b64 s[26:27], s[4:5], exec
	s_cselect_b32 s15, s21, s25
	s_cselect_b32 s44, s20, s24
	s_add_u32 s22, s22, 0x40080
	s_addc_u32 s23, s23, 0
	s_add_u32 s45, s24, 0x100
	v_mov_b32_e32 v0, 0
	s_addc_u32 s46, s25, 0
	s_mov_b32 s47, -2
	v_mov_b32_e32 v1, v0
	v_mov_b32_e32 v2, v0
	v_mov_b32_e32 v3, v0
	v_mov_b32_e32 v4, v0
	v_mov_b32_e32 v5, v0
	v_mov_b32_e32 v6, v0
	v_mov_b32_e32 v7, v0
	v_mov_b32_e32 v16, v0
	v_mov_b32_e32 v17, v0
	v_mov_b32_e32 v18, v0
	v_mov_b32_e32 v19, v0
	v_mov_b32_e32 v20, v0
	v_mov_b32_e32 v21, v0
	v_mov_b32_e32 v22, v0
	v_mov_b32_e32 v23, v0
	v_mov_b32_e32 v32, v0
	v_mov_b32_e32 v33, v0
	v_mov_b32_e32 v34, v0
	v_mov_b32_e32 v35, v0
	v_mov_b32_e32 v36, v0
	v_mov_b32_e32 v37, v0
	v_mov_b32_e32 v38, v0
	v_mov_b32_e32 v39, v0
	v_mov_b32_e32 v48, v0
	v_mov_b32_e32 v49, v0
	v_mov_b32_e32 v50, v0
	v_mov_b32_e32 v51, v0
	v_mov_b32_e32 v52, v0
	v_mov_b32_e32 v53, v0
	v_mov_b32_e32 v54, v0
	v_mov_b32_e32 v55, v0
	v_mov_b32_e32 v8, v0
	v_mov_b32_e32 v9, v0
	v_mov_b32_e32 v10, v0
	v_mov_b32_e32 v11, v0
	v_mov_b32_e32 v12, v0
	v_mov_b32_e32 v13, v0
	v_mov_b32_e32 v14, v0
	v_mov_b32_e32 v15, v0
	v_mov_b32_e32 v24, v0
	v_mov_b32_e32 v25, v0
	v_mov_b32_e32 v26, v0
	v_mov_b32_e32 v27, v0
	v_mov_b32_e32 v28, v0
	v_mov_b32_e32 v29, v0
	v_mov_b32_e32 v30, v0
	v_mov_b32_e32 v31, v0
	v_mov_b32_e32 v40, v0
	v_mov_b32_e32 v41, v0
	v_mov_b32_e32 v42, v0
	v_mov_b32_e32 v43, v0
	v_mov_b32_e32 v44, v0
	v_mov_b32_e32 v45, v0
	v_mov_b32_e32 v46, v0
	v_mov_b32_e32 v47, v0
	v_mov_b32_e32 v56, v0
	v_mov_b32_e32 v57, v0
	v_mov_b32_e32 v58, v0
	v_mov_b32_e32 v59, v0
	v_mov_b32_e32 v60, v0
	v_mov_b32_e32 v61, v0
	v_mov_b32_e32 v62, v0
	v_mov_b32_e32 v63, v0
	v_mov_b32_e32 v64, v0
	v_mov_b32_e32 v65, v0
	v_mov_b32_e32 v66, v0
	v_mov_b32_e32 v67, v0
	v_mov_b32_e32 v68, v0
	v_mov_b32_e32 v69, v0
	v_mov_b32_e32 v70, v0
	v_mov_b32_e32 v71, v0
	v_mov_b32_e32 v80, v0
	v_mov_b32_e32 v81, v0
	v_mov_b32_e32 v82, v0
	v_mov_b32_e32 v83, v0
	v_mov_b32_e32 v84, v0
	v_mov_b32_e32 v85, v0
	v_mov_b32_e32 v86, v0
	v_mov_b32_e32 v87, v0
	v_mov_b32_e32 v96, v0
	v_mov_b32_e32 v97, v0
	v_mov_b32_e32 v98, v0
	v_mov_b32_e32 v99, v0
	v_mov_b32_e32 v100, v0
	v_mov_b32_e32 v101, v0
	v_mov_b32_e32 v102, v0
	v_mov_b32_e32 v103, v0
	v_mov_b32_e32 v112, v0
	v_mov_b32_e32 v113, v0
	v_mov_b32_e32 v114, v0
	v_mov_b32_e32 v115, v0
	v_mov_b32_e32 v116, v0
	v_mov_b32_e32 v117, v0
	v_mov_b32_e32 v118, v0
	v_mov_b32_e32 v119, v0
	v_mov_b32_e32 v72, v0
	v_mov_b32_e32 v73, v0
	v_mov_b32_e32 v74, v0
	v_mov_b32_e32 v75, v0
	v_mov_b32_e32 v76, v0
	v_mov_b32_e32 v77, v0
	v_mov_b32_e32 v78, v0
	v_mov_b32_e32 v79, v0
	v_mov_b32_e32 v88, v0
	v_mov_b32_e32 v89, v0
	v_mov_b32_e32 v90, v0
	v_mov_b32_e32 v91, v0
	v_mov_b32_e32 v92, v0
	v_mov_b32_e32 v93, v0
	v_mov_b32_e32 v94, v0
	v_mov_b32_e32 v95, v0
	v_mov_b32_e32 v104, v0
	v_mov_b32_e32 v105, v0
	v_mov_b32_e32 v106, v0
	v_mov_b32_e32 v107, v0
	v_mov_b32_e32 v108, v0
	v_mov_b32_e32 v109, v0
	v_mov_b32_e32 v110, v0
	v_mov_b32_e32 v111, v0
	v_mov_b32_e32 v120, v0
	v_mov_b32_e32 v121, v0
	v_mov_b32_e32 v122, v0
	v_mov_b32_e32 v123, v0
	v_mov_b32_e32 v124, v0
	v_mov_b32_e32 v125, v0
	v_mov_b32_e32 v126, v0
	v_mov_b32_e32 v127, v0
	.p2align 6

.LBB0_650:
	s_ashr_i32 s17, s16, 31
	s_lshl_b64 s[18:19], s[16:17], 19
	s_add_u32 s18, s26, s18
	s_addc_u32 s19, s27, s19
	s_and_b64 s[20:21], s[6:7], exec
	s_cselect_b32 s17, s19, s3
	s_cselect_b32 s41, s18, s2
	s_ashr_i32 s15, s14, 31
	s_lshl_b64 s[20:21], s[14:15], 19
	s_add_u32 s20, s28, s20
	s_addc_u32 s21, s29, s21
	s_and_b64 s[24:25], s[6:7], exec
	s_cselect_b32 s15, s21, s23
	s_cselect_b32 s42, s20, s22
	s_add_u32 s2, s2, 0x40080
	s_addc_u32 s3, s3, 0
	s_add_u32 s43, s22, 0x100
	v_mov_b32_e32 v0, 0
	s_addc_u32 s44, s23, 0
	s_mov_b32 s45, -2
	v_mov_b32_e32 v1, v0
	v_mov_b32_e32 v2, v0
	v_mov_b32_e32 v3, v0
	v_mov_b32_e32 v4, v0
	v_mov_b32_e32 v5, v0
	v_mov_b32_e32 v6, v0
	v_mov_b32_e32 v7, v0
	v_mov_b32_e32 v16, v0
	v_mov_b32_e32 v17, v0
	v_mov_b32_e32 v18, v0
	v_mov_b32_e32 v19, v0
	v_mov_b32_e32 v20, v0
	v_mov_b32_e32 v21, v0
	v_mov_b32_e32 v22, v0
	v_mov_b32_e32 v23, v0
	v_mov_b32_e32 v32, v0
	v_mov_b32_e32 v33, v0
	v_mov_b32_e32 v34, v0
	v_mov_b32_e32 v35, v0
	v_mov_b32_e32 v36, v0
	v_mov_b32_e32 v37, v0
	v_mov_b32_e32 v38, v0
	v_mov_b32_e32 v39, v0
	v_mov_b32_e32 v48, v0
	v_mov_b32_e32 v49, v0
	v_mov_b32_e32 v50, v0
	v_mov_b32_e32 v51, v0
	v_mov_b32_e32 v52, v0
	v_mov_b32_e32 v53, v0
	v_mov_b32_e32 v54, v0
	v_mov_b32_e32 v55, v0
	v_mov_b32_e32 v8, v0
	v_mov_b32_e32 v9, v0
	v_mov_b32_e32 v10, v0
	v_mov_b32_e32 v11, v0
	v_mov_b32_e32 v12, v0
	v_mov_b32_e32 v13, v0
	v_mov_b32_e32 v14, v0
	v_mov_b32_e32 v15, v0
	v_mov_b32_e32 v24, v0
	v_mov_b32_e32 v25, v0
	v_mov_b32_e32 v26, v0
	v_mov_b32_e32 v27, v0
	v_mov_b32_e32 v28, v0
	v_mov_b32_e32 v29, v0
	v_mov_b32_e32 v30, v0
	v_mov_b32_e32 v31, v0
	v_mov_b32_e32 v40, v0
	v_mov_b32_e32 v41, v0
	v_mov_b32_e32 v42, v0
	v_mov_b32_e32 v43, v0
	v_mov_b32_e32 v44, v0
	v_mov_b32_e32 v45, v0
	v_mov_b32_e32 v46, v0
	v_mov_b32_e32 v47, v0
	v_mov_b32_e32 v56, v0
	v_mov_b32_e32 v57, v0
	v_mov_b32_e32 v58, v0
	v_mov_b32_e32 v59, v0
	v_mov_b32_e32 v60, v0
	v_mov_b32_e32 v61, v0
	v_mov_b32_e32 v62, v0
	v_mov_b32_e32 v63, v0
	v_mov_b32_e32 v64, v0
	v_mov_b32_e32 v65, v0
	v_mov_b32_e32 v66, v0
	v_mov_b32_e32 v67, v0
	v_mov_b32_e32 v68, v0
	v_mov_b32_e32 v69, v0
	v_mov_b32_e32 v70, v0
	v_mov_b32_e32 v71, v0
	v_mov_b32_e32 v80, v0
	v_mov_b32_e32 v81, v0
	v_mov_b32_e32 v82, v0
	v_mov_b32_e32 v83, v0
	v_mov_b32_e32 v84, v0
	v_mov_b32_e32 v85, v0
	v_mov_b32_e32 v86, v0
	v_mov_b32_e32 v87, v0
	v_mov_b32_e32 v96, v0
	v_mov_b32_e32 v97, v0
	v_mov_b32_e32 v98, v0
	v_mov_b32_e32 v99, v0
	v_mov_b32_e32 v100, v0
	v_mov_b32_e32 v101, v0
	v_mov_b32_e32 v102, v0
	v_mov_b32_e32 v103, v0
	v_mov_b32_e32 v112, v0
	v_mov_b32_e32 v113, v0
	v_mov_b32_e32 v114, v0
	v_mov_b32_e32 v115, v0
	v_mov_b32_e32 v116, v0
	v_mov_b32_e32 v117, v0
	v_mov_b32_e32 v118, v0
	v_mov_b32_e32 v119, v0
	v_mov_b32_e32 v72, v0
	v_mov_b32_e32 v73, v0
	v_mov_b32_e32 v74, v0
	v_mov_b32_e32 v75, v0
	v_mov_b32_e32 v76, v0
	v_mov_b32_e32 v77, v0
	v_mov_b32_e32 v78, v0
	v_mov_b32_e32 v79, v0
	v_mov_b32_e32 v88, v0
	v_mov_b32_e32 v89, v0
	v_mov_b32_e32 v90, v0
	v_mov_b32_e32 v91, v0
	v_mov_b32_e32 v92, v0
	v_mov_b32_e32 v93, v0
	v_mov_b32_e32 v94, v0
	v_mov_b32_e32 v95, v0
	v_mov_b32_e32 v104, v0
	v_mov_b32_e32 v105, v0
	v_mov_b32_e32 v106, v0
	v_mov_b32_e32 v107, v0
	v_mov_b32_e32 v108, v0
	v_mov_b32_e32 v109, v0
	v_mov_b32_e32 v110, v0
	v_mov_b32_e32 v111, v0
	v_mov_b32_e32 v120, v0
	v_mov_b32_e32 v121, v0
	v_mov_b32_e32 v122, v0
	v_mov_b32_e32 v123, v0
	v_mov_b32_e32 v124, v0
	v_mov_b32_e32 v125, v0
	v_mov_b32_e32 v126, v0
	v_mov_b32_e32 v127, v0
	.p2align 6

.LBB0_723:
	s_ashr_i32 s13, s12, 31
	s_lshl_b64 s[14:15], s[12:13], 19
	s_add_u32 s14, s24, s14
	s_addc_u32 s15, s25, s15
	s_and_b64 s[16:17], s[4:5], exec
	s_cselect_b32 s13, s15, s19
	s_cselect_b32 s39, s14, s18
	s_ashr_i32 s11, s10, 31
	s_lshl_b64 s[16:17], s[10:11], 19
	s_add_u32 s16, s26, s16
	s_addc_u32 s17, s27, s17
	s_and_b64 s[22:23], s[4:5], exec
	s_cselect_b32 s11, s17, s21
	s_cselect_b32 s40, s16, s20
	s_add_u32 s18, s18, 0x40080
	s_addc_u32 s19, s19, 0
	s_add_u32 s41, s20, 0x100
	v_mov_b32_e32 v0, 0
	s_addc_u32 s42, s21, 0
	s_mov_b32 s43, -2
	v_mov_b32_e32 v1, v0
	v_mov_b32_e32 v2, v0
	v_mov_b32_e32 v3, v0
	v_mov_b32_e32 v4, v0
	v_mov_b32_e32 v5, v0
	v_mov_b32_e32 v6, v0
	v_mov_b32_e32 v7, v0
	v_mov_b32_e32 v16, v0
	v_mov_b32_e32 v17, v0
	v_mov_b32_e32 v18, v0
	v_mov_b32_e32 v19, v0
	v_mov_b32_e32 v20, v0
	v_mov_b32_e32 v21, v0
	v_mov_b32_e32 v22, v0
	v_mov_b32_e32 v23, v0
	v_mov_b32_e32 v32, v0
	v_mov_b32_e32 v33, v0
	v_mov_b32_e32 v34, v0
	v_mov_b32_e32 v35, v0
	v_mov_b32_e32 v36, v0
	v_mov_b32_e32 v37, v0
	v_mov_b32_e32 v38, v0
	v_mov_b32_e32 v39, v0
	v_mov_b32_e32 v48, v0
	v_mov_b32_e32 v49, v0
	v_mov_b32_e32 v50, v0
	v_mov_b32_e32 v51, v0
	v_mov_b32_e32 v52, v0
	v_mov_b32_e32 v53, v0
	v_mov_b32_e32 v54, v0
	v_mov_b32_e32 v55, v0
	v_mov_b32_e32 v8, v0
	v_mov_b32_e32 v9, v0
	v_mov_b32_e32 v10, v0
	v_mov_b32_e32 v11, v0
	v_mov_b32_e32 v12, v0
	v_mov_b32_e32 v13, v0
	v_mov_b32_e32 v14, v0
	v_mov_b32_e32 v15, v0
	v_mov_b32_e32 v24, v0
	v_mov_b32_e32 v25, v0
	v_mov_b32_e32 v26, v0
	v_mov_b32_e32 v27, v0
	v_mov_b32_e32 v28, v0
	v_mov_b32_e32 v29, v0
	v_mov_b32_e32 v30, v0
	v_mov_b32_e32 v31, v0
	v_mov_b32_e32 v40, v0
	v_mov_b32_e32 v41, v0
	v_mov_b32_e32 v42, v0
	v_mov_b32_e32 v43, v0
	v_mov_b32_e32 v44, v0
	v_mov_b32_e32 v45, v0
	v_mov_b32_e32 v46, v0
	v_mov_b32_e32 v47, v0
	v_mov_b32_e32 v56, v0
	v_mov_b32_e32 v57, v0
	v_mov_b32_e32 v58, v0
	v_mov_b32_e32 v59, v0
	v_mov_b32_e32 v60, v0
	v_mov_b32_e32 v61, v0
	v_mov_b32_e32 v62, v0
	v_mov_b32_e32 v63, v0
	v_mov_b32_e32 v64, v0
	v_mov_b32_e32 v65, v0
	v_mov_b32_e32 v66, v0
	v_mov_b32_e32 v67, v0
	v_mov_b32_e32 v68, v0
	v_mov_b32_e32 v69, v0
	v_mov_b32_e32 v70, v0
	v_mov_b32_e32 v71, v0
	v_mov_b32_e32 v80, v0
	v_mov_b32_e32 v81, v0
	v_mov_b32_e32 v82, v0
	v_mov_b32_e32 v83, v0
	v_mov_b32_e32 v84, v0
	v_mov_b32_e32 v85, v0
	v_mov_b32_e32 v86, v0
	v_mov_b32_e32 v87, v0
	v_mov_b32_e32 v96, v0
	v_mov_b32_e32 v97, v0
	v_mov_b32_e32 v98, v0
	v_mov_b32_e32 v99, v0
	v_mov_b32_e32 v100, v0
	v_mov_b32_e32 v101, v0
	v_mov_b32_e32 v102, v0
	v_mov_b32_e32 v103, v0
	v_mov_b32_e32 v112, v0
	v_mov_b32_e32 v113, v0
	v_mov_b32_e32 v114, v0
	v_mov_b32_e32 v115, v0
	v_mov_b32_e32 v116, v0
	v_mov_b32_e32 v117, v0
	v_mov_b32_e32 v118, v0
	v_mov_b32_e32 v119, v0
	v_mov_b32_e32 v72, v0
	v_mov_b32_e32 v73, v0
	v_mov_b32_e32 v74, v0
	v_mov_b32_e32 v75, v0
	v_mov_b32_e32 v76, v0
	v_mov_b32_e32 v77, v0
	v_mov_b32_e32 v78, v0
	v_mov_b32_e32 v79, v0
	v_mov_b32_e32 v88, v0
	v_mov_b32_e32 v89, v0
	v_mov_b32_e32 v90, v0
	v_mov_b32_e32 v91, v0
	v_mov_b32_e32 v92, v0
	v_mov_b32_e32 v93, v0
	v_mov_b32_e32 v94, v0
	v_mov_b32_e32 v95, v0
	v_mov_b32_e32 v104, v0
	v_mov_b32_e32 v105, v0
	v_mov_b32_e32 v106, v0
	v_mov_b32_e32 v107, v0
	v_mov_b32_e32 v108, v0
	v_mov_b32_e32 v109, v0
	v_mov_b32_e32 v110, v0
	v_mov_b32_e32 v111, v0
	v_mov_b32_e32 v120, v0
	v_mov_b32_e32 v121, v0
	v_mov_b32_e32 v122, v0
	v_mov_b32_e32 v123, v0
	v_mov_b32_e32 v124, v0
	v_mov_b32_e32 v125, v0
	v_mov_b32_e32 v126, v0
	v_mov_b32_e32 v127, v0
	.p2align 6
